# grid barrier: shorter dependency chain (XCD last arriver releases and bumps one top counter, all poll it)
# speedup vs baseline: 1.0051x; 1.0051x over previous
.LBB0_112:
	s_waitcnt vmcnt(0)
	s_barrier
	s_mov_b64 s[0:1], exec
	v_readlane_b32 s2, v252, 9
	v_readlane_b32 s3, v252, 10
	s_and_b64 s[2:3], s[0:1], s[2:3]
	s_mov_b64 exec, s[2:3]
	s_cbranch_execz .LBB0_164
	v_readlane_b32 s30, v252, 11
	v_readlane_b32 s31, v252, 12
	v_readlane_b32 s32, v252, 13
	v_mov_b32_e32 v5, 1
	v_mov_b32_e32 v22, 0
	s_add_u32 s34, s30, 0x1400
	s_addc_u32 s35, s31, 0
	s_lshl_b32 s32, s32, 8
	s_add_u32 s40, s30, 0x3400
	s_addc_u32 s41, s31, 0
	v_mov_b32_e32 v4, s32
	s_mov_b32 s42, 0
	s_add_u32 s36, s30, 0x400
	s_addc_u32 s37, s31, 0
.Lxb1_census:
	global_load_dword v6, v22, s[36:37] sc1
	global_load_dword v7, v22, s[36:37] offset:256 sc1
	global_load_dword v8, v22, s[36:37] offset:512 sc1
	global_load_dword v9, v22, s[36:37] offset:768 sc1
	global_load_dword v10, v22, s[36:37] offset:1024 sc1
	global_load_dword v11, v22, s[36:37] offset:1280 sc1
	global_load_dword v12, v22, s[36:37] offset:1536 sc1
	global_load_dword v13, v22, s[36:37] offset:1792 sc1
	global_load_dword v14, v22, s[36:37] offset:2048 sc1
	global_load_dword v15, v22, s[36:37] offset:2304 sc1
	global_load_dword v16, v22, s[36:37] offset:2560 sc1
	global_load_dword v17, v22, s[36:37] offset:2816 sc1
	global_load_dword v18, v22, s[36:37] offset:3072 sc1
	global_load_dword v19, v22, s[36:37] offset:3328 sc1
	global_load_dword v20, v22, s[36:37] offset:3584 sc1
	global_load_dword v21, v22, s[36:37] offset:3840 sc1
	global_load_dword v28, v4, s[36:37] sc1
	s_waitcnt vmcnt(0)
	v_add3_u32 v23, v6, v7, v8
	v_add3_u32 v24, v9, v10, v11
	v_add3_u32 v25, v12, v13, v14
	v_add3_u32 v26, v15, v16, v17
	v_add3_u32 v27, v18, v19, v20
	v_add3_u32 v23, v23, v24, v25
	v_add3_u32 v26, v26, v27, v21
	v_add_u32_e32 v23, v23, v26
	v_cmp_eq_u32_e32 vcc, s86, v23
	s_cbranch_vccnz .Lxb1_census_done
	s_add_i32 s42, s42, 1
	s_cmp_lt_u32 s42, 0x200000
	s_cbranch_scc0 .Lxb1_census_done
	s_sleep 1
	s_branch .Lxb1_census
.Lxb1_census_done:
	v_readfirstlane_b32 s98, v28
	s_mov_b32 s42, 0
	global_atomic_add v6, v4, v5, s[34:35] sc0
	s_mul_i32 s33, s86, 1
	s_mul_i32 s39, s98, 1
	s_waitcnt vmcnt(0)
	v_readfirstlane_b32 s38, v6
	v_mov_b32_e32 v7, s98
	s_add_i32 s38, s38, 1
	s_cmp_lg_u32 s38, s39
	s_cbranch_scc1 .Lxb1_spin
	buffer_wbl2 sc1
	s_waitcnt vmcnt(0)
	global_atomic_add v22, v7, s[40:41]
.Lxb1_spin:
	global_load_dword v8, v22, s[40:41] sc1
	s_waitcnt vmcnt(0)
	v_cmp_le_u32_e32 vcc, s33, v8
	s_cbranch_vccnz .Lxb1_done
	s_add_i32 s42, s42, 1
	s_cmp_lt_u32 s42, 0x400000
	s_cbranch_scc0 .Lxb1_done
	s_sleep 1
	s_branch .Lxb1_spin
.Lxb1_done:
	buffer_inv sc1
	s_waitcnt vmcnt(0)

.LBB0_307:
	s_waitcnt vmcnt(0)
	s_barrier
	s_mov_b64 s[0:1], exec
	v_readlane_b32 s2, v252, 9
	v_readlane_b32 s3, v252, 10
	s_and_b64 s[2:3], s[0:1], s[2:3]
	s_mov_b64 exec, s[2:3]
	s_cbranch_execz .LBB0_359
	v_readlane_b32 s30, v252, 11
	v_readlane_b32 s31, v252, 12
	v_readlane_b32 s32, v252, 13
	v_mov_b32_e32 v5, 1
	v_mov_b32_e32 v22, 0
	s_add_u32 s34, s30, 0x1400
	s_addc_u32 s35, s31, 0
	s_lshl_b32 s32, s32, 8
	s_add_u32 s40, s30, 0x3400
	s_addc_u32 s41, s31, 0
	v_mov_b32_e32 v4, s32
	s_mov_b32 s42, 0
	global_atomic_add v6, v4, v5, s[34:35] sc0
	s_mul_i32 s33, s86, 2
	s_mul_i32 s39, s98, 2
	s_waitcnt vmcnt(0)
	v_readfirstlane_b32 s38, v6
	v_mov_b32_e32 v7, s98
	s_add_i32 s38, s38, 1
	s_cmp_lg_u32 s38, s39
	s_cbranch_scc1 .Lxb2_spin
	buffer_wbl2 sc1
	s_waitcnt vmcnt(0)
	global_atomic_add v22, v7, s[40:41]

.LBB0_610:
	s_waitcnt vmcnt(0)
	s_barrier
	s_mov_b64 s[0:1], exec
	v_readlane_b32 s2, v252, 9
	v_readlane_b32 s3, v252, 10
	s_and_b64 s[2:3], s[0:1], s[2:3]
	s_mov_b64 exec, s[2:3]
	s_cbranch_execz .LBB0_662
	v_readlane_b32 s30, v252, 11
	v_readlane_b32 s31, v252, 12
	v_readlane_b32 s32, v252, 13
	v_mov_b32_e32 v5, 1
	v_mov_b32_e32 v22, 0
	s_add_u32 s34, s30, 0x1400
	s_addc_u32 s35, s31, 0
	s_lshl_b32 s32, s32, 8
	s_add_u32 s40, s30, 0x3400
	s_addc_u32 s41, s31, 0
	v_mov_b32_e32 v4, s32
	s_mov_b32 s42, 0
	global_atomic_add v6, v4, v5, s[34:35] sc0
	s_mul_i32 s33, s86, 3
	s_mul_i32 s39, s98, 3
	s_waitcnt vmcnt(0)
	v_readfirstlane_b32 s38, v6
	v_mov_b32_e32 v7, s98
	s_add_i32 s38, s38, 1
	s_cmp_lg_u32 s38, s39
	s_cbranch_scc1 .Lxb3_spin
	buffer_wbl2 sc1
	s_waitcnt vmcnt(0)
	global_atomic_add v22, v7, s[40:41]

.LBB0_724:
	s_waitcnt vmcnt(0)
	s_barrier
	s_mov_b64 s[0:1], exec
	v_readlane_b32 s2, v252, 9
	v_readlane_b32 s3, v252, 10
	s_and_b64 s[2:3], s[0:1], s[2:3]
	s_mov_b64 exec, s[2:3]
	s_cbranch_execz .LBB0_776
	v_readlane_b32 s30, v252, 11
	v_readlane_b32 s31, v252, 12
	v_readlane_b32 s32, v252, 13
	v_mov_b32_e32 v5, 1
	v_mov_b32_e32 v22, 0
	s_add_u32 s34, s30, 0x1400
	s_addc_u32 s35, s31, 0
	s_lshl_b32 s32, s32, 8
	s_add_u32 s40, s30, 0x3400
	s_addc_u32 s41, s31, 0
	v_mov_b32_e32 v4, s32
	s_mov_b32 s42, 0
	global_atomic_add v6, v4, v5, s[34:35] sc0
	s_mul_i32 s33, s86, 4
	s_mul_i32 s39, s98, 4
	s_waitcnt vmcnt(0)
	v_readfirstlane_b32 s38, v6
	v_mov_b32_e32 v7, s98
	s_add_i32 s38, s38, 1
	s_cmp_lg_u32 s38, s39
	s_cbranch_scc1 .Lxb4_spin
	buffer_wbl2 sc1
	s_waitcnt vmcnt(0)
	global_atomic_add v22, v7, s[40:41]

.LBB0_1008:
	s_waitcnt vmcnt(0)
	s_barrier
	s_mov_b64 s[0:1], exec
	v_readlane_b32 s2, v252, 9
	v_readlane_b32 s3, v252, 10
	s_and_b64 s[2:3], s[0:1], s[2:3]
	s_mov_b64 exec, s[2:3]
	s_cbranch_execz .LBB0_1060
	v_readlane_b32 s30, v252, 11
	v_readlane_b32 s31, v252, 12
	v_readlane_b32 s32, v252, 13
	v_mov_b32_e32 v5, 1
	v_mov_b32_e32 v22, 0
	s_add_u32 s34, s30, 0x1400
	s_addc_u32 s35, s31, 0
	s_lshl_b32 s32, s32, 8
	s_add_u32 s40, s30, 0x3400
	s_addc_u32 s41, s31, 0
	v_mov_b32_e32 v4, s32
	s_mov_b32 s42, 0
	global_atomic_add v6, v4, v5, s[34:35] sc0
	s_mul_i32 s33, s86, 5
	s_mul_i32 s39, s98, 5
	s_waitcnt vmcnt(0)
	v_readfirstlane_b32 s38, v6
	v_mov_b32_e32 v7, s98
	s_add_i32 s38, s38, 1
	s_cmp_lg_u32 s38, s39
	s_cbranch_scc1 .Lxb5_spin
	buffer_wbl2 sc1
	s_waitcnt vmcnt(0)
	global_atomic_add v22, v7, s[40:41]

.LBB0_1091:
	s_waitcnt vmcnt(0)
	s_barrier
	s_mov_b64 s[0:1], exec
	v_readlane_b32 s6, v252, 9
	v_readlane_b32 s7, v252, 10
	s_and_b64 s[6:7], s[0:1], s[6:7]
	s_mov_b64 exec, s[6:7]
	s_cbranch_execz .LBB0_1143
	v_readlane_b32 s30, v252, 11
	v_readlane_b32 s31, v252, 12
	v_readlane_b32 s32, v252, 13
	v_mov_b32_e32 v5, 1
	v_mov_b32_e32 v22, 0
	s_add_u32 s34, s30, 0x1400
	s_addc_u32 s35, s31, 0
	s_lshl_b32 s32, s32, 8
	s_add_u32 s40, s30, 0x3400
	s_addc_u32 s41, s31, 0
	v_mov_b32_e32 v4, s32
	s_mov_b32 s42, 0
	global_atomic_add v6, v4, v5, s[34:35] sc0
	s_mul_i32 s33, s86, 6
	s_mul_i32 s39, s98, 6
	s_waitcnt vmcnt(0)
	v_readfirstlane_b32 s38, v6
	v_mov_b32_e32 v7, s98
	s_add_i32 s38, s38, 1
	s_cmp_lg_u32 s38, s39
	s_cbranch_scc1 .Lxb6_spin
	buffer_wbl2 sc1
	s_waitcnt vmcnt(0)
	global_atomic_add v22, v7, s[40:41]

	.amdhsa_kernel _Z14fwd_megakernel3Ctx
		.amdhsa_group_segment_fixed_size 0
		.amdhsa_private_segment_fixed_size 0
		.amdhsa_kernarg_size 416
		.amdhsa_user_sgpr_count 2
		.amdhsa_user_sgpr_dispatch_ptr 0
		.amdhsa_user_sgpr_queue_ptr 0
		.amdhsa_user_sgpr_kernarg_segment_ptr 1
		.amdhsa_user_sgpr_dispatch_id 0
		.amdhsa_user_sgpr_kernarg_preload_length 0
		.amdhsa_user_sgpr_kernarg_preload_offset 0
		.amdhsa_user_sgpr_private_segment_size 0
		.amdhsa_uses_dynamic_stack 0
		.amdhsa_enable_private_segment 0
		.amdhsa_system_sgpr_workgroup_id_x 1
		.amdhsa_system_sgpr_workgroup_id_y 0
		.amdhsa_system_sgpr_workgroup_id_z 0
		.amdhsa_system_sgpr_workgroup_info 0
		.amdhsa_system_vgpr_workitem_id 2
		.amdhsa_next_free_vgpr 253
		.amdhsa_next_free_sgpr 99
		.amdhsa_accum_offset 256
		.amdhsa_reserve_vcc 1
		.amdhsa_float_round_mode_32 0
		.amdhsa_float_round_mode_16_64 0
		.amdhsa_float_denorm_mode_32 3
		.amdhsa_float_denorm_mode_16_64 3
		.amdhsa_dx10_clamp 1
		.amdhsa_ieee_mode 1
		.amdhsa_fp16_overflow 0
		.amdhsa_tg_split 0
		.amdhsa_exception_fp_ieee_invalid_op 0
		.amdhsa_exception_fp_denorm_src 0
		.amdhsa_exception_fp_ieee_div_zero 0
		.amdhsa_exception_fp_ieee_overflow 0
		.amdhsa_exception_fp_ieee_underflow 0
		.amdhsa_exception_fp_ieee_inexact 0
		.amdhsa_exception_int_div_zero 0
	.end_amdhsa_kernel

amdhsa.kernels:
  - .agpr_count:     0
    .args:
      - .offset:         0
        .size:           160
        .value_kind:     by_value
      - .offset:         160
        .size:           4
        .value_kind:     hidden_block_count_x
      - .offset:         164
        .size:           4
        .value_kind:     hidden_block_count_y
      - .offset:         168
        .size:           4
        .value_kind:     hidden_block_count_z
      - .offset:         172
        .size:           2
        .value_kind:     hidden_group_size_x
      - .offset:         174
        .size:           2
        .value_kind:     hidden_group_size_y
      - .offset:         176
        .size:           2
        .value_kind:     hidden_group_size_z
      - .offset:         178
        .size:           2
        .value_kind:     hidden_remainder_x
      - .offset:         180
        .size:           2
        .value_kind:     hidden_remainder_y
      - .offset:         182
        .size:           2
        .value_kind:     hidden_remainder_z
      - .offset:         200
        .size:           8
        .value_kind:     hidden_global_offset_x
      - .offset:         208
        .size:           8
        .value_kind:     hidden_global_offset_y
      - .offset:         216
        .size:           8
        .value_kind:     hidden_global_offset_z
      - .offset:         224
        .size:           2
        .value_kind:     hidden_grid_dims
      - .offset:         248
        .size:           8
        .value_kind:     hidden_multigrid_sync_arg
      - .offset:         280
        .size:           4
        .value_kind:     hidden_dynamic_lds_size
    .group_segment_fixed_size: 0
    .kernarg_segment_align: 8
    .kernarg_segment_size: 416
    .language:       OpenCL C
    .language_version:
      - 2
      - 0
    .max_flat_workgroup_size: 512
    .name:           _Z14fwd_megakernel3Ctx
    .private_segment_fixed_size: 0
    .sgpr_count:     105
    .sgpr_spill_count: 59
    .symbol:         _Z14fwd_megakernel3Ctx.kd
    .uniform_work_group_size: 1
    .uses_dynamic_stack: false
    .vgpr_count:     253
    .vgpr_spill_count: 0
    .wavefront_size: 64
